# phase-8 NA bias-table staging: 4 loads per thread in flight (was waits after every pair), on top of v29
# baseline (speedup 1.0000x reference)
; #define LAS __attribute__((address_space(3)))
; __global__ void __launch_bounds__(NTHR) fwd_megakernel(Args a_unused) {
;     ...
;                 LAS float* rpbl = (LAS float*)(lds + 49152);
;                 for (int i = tid; i < 4 * 465; i += NTHR) rpbl[i] = a->in[27][l * 4 * 465 + i] * LOG2E;
;                 __syncthreads();
.LBB0_245:
	v_mbcnt_lo_u32_b32 v1, -1, 0
	v_mbcnt_hi_u32_b32 v1, -1, v1
	s_load_dwordx2 s[2:3], s[30:31], 0xd8
	v_add_u32_e32 v2, s63, v1
	v_lshlrev_b32_e32 v3, 2, v2
	s_mul_i32 s12, s62, 0x1d10
	s_waitcnt lgkmcnt(0)
	s_add_u32 s2, s2, s12
	s_addc_u32 s3, s3, 0
	global_load_dword v4, v3, s[2:3]
	global_load_dword v5, v3, s[2:3] offset:2048
	s_add_u32 s2, s2, 0x1000
	s_addc_u32 s3, s3, 0
	global_load_dword v6, v3, s[2:3]
	v_add_u32_e32 v8, 0xc000, v3
	s_movk_i32 s12, 0x144
	v_cmp_gt_i32_e32 vcc, s12, v2
	s_and_saveexec_b64 s[0:1], vcc
	global_load_dword v7, v3, s[2:3] offset:2048
	s_waitcnt vmcnt(0)
	v_mul_f32_e32 v7, 0x3fb8aa3b, v7
	ds_write_b32 v8, v7 offset:6144
	s_or_b64 exec, exec, s[0:1]
	s_waitcnt vmcnt(0)
	v_mul_f32_e32 v4, 0x3fb8aa3b, v4
	v_mul_f32_e32 v5, 0x3fb8aa3b, v5
	v_mul_f32_e32 v6, 0x3fb8aa3b, v6
	ds_write_b32 v8, v4
	ds_write_b32 v8, v5 offset:2048
	ds_write_b32 v8, v6 offset:4096
